# previous best + rw_scan final state update issues the hi pair first so the next step's first product waits on one fewer instruction
# speedup vs baseline: 1.0144x; 1.0040x over previous
.LBB0_774:
	s_and_b32 s11, s10, 1
	s_mul_i32 s0, s11, 0x5400
	s_add_i32 s0, s0, 16
	v_lshl_add_u32 v126, v87, 2, s0
	v_add3_u32 v124, s0, v91, v92
	s_lshl_b32 s0, s11, 10
	s_add_i32 s0, s0, 0xe810
	v_add_u32_e32 v127, v91, v92
	v_lshl_add_u32 v127, v127, 4, s0
	ds_read_b128 v[136:139], v127 offset:0
	ds_read_b128 v[184:187], v126 offset:0
	ds_read_b128 v[196:199], v126 offset:768
	ds_read_b128 v[188:191], v126 offset:256
	ds_read_b128 v[200:203], v126 offset:1024
	ds_read_b128 v[192:195], v126 offset:512
	ds_read_b128 v[206:209], v126 offset:1344
	ds_read_b128 v[218:221], v126 offset:2112
	ds_read_b128 v[210:213], v126 offset:1600
	ds_read_b128 v[222:225], v126 offset:2368
	ds_read_b128 v[214:217], v126 offset:1856
	s_waitcnt lgkmcnt(5)
	v_pk_mul_f32 v[250:251], v[8:9], v[184:185]
	v_pk_mul_f32 v[252:253], v[136:137], v[196:197] op_sel_hi:[0,1]
	v_pk_fma_f32 v[250:251], v[10:11], v[186:187], v[250:251]
	v_pk_mul_f32 v[254:255], v[136:137], v[198:199] op_sel_hi:[0,1]
	v_add_f32_e32 v14, v250, v251
	v_pk_fma_f32 v[252:253], v[8:9], v[188:189], v[252:253]
	v_pk_fma_f32 v[254:255], v[10:11], v[190:191], v[254:255]
	v_add_f32_dpp v14, v14, v14 quad_perm:[1,0,3,2] row_mask:0xf bank_mask:0xf bound_ctrl:1
	ds_read_b128 v[228:231], v126 offset:2688
	ds_read_b128 v[240:243], v126 offset:3456
	v_add_f32_dpp v14, v14, v14 quad_perm:[2,3,0,1] row_mask:0xf bank_mask:0xf bound_ctrl:1
	ds_read_b128 v[232:235], v126 offset:2944
	ds_read_b128 v[244:247], v126 offset:3712
	v_add_f32_dpp v14, v14, v14 row_half_mirror row_mask:0xf bank_mask:0xf bound_ctrl:1
	ds_read_b128 v[236:239], v126 offset:3200
	s_nop 0
	v_add_f32_dpp v14, v14, v14 row_mirror row_mask:0xf bank_mask:0xf bound_ctrl:1
	v_pk_fma_f32 v[10:11], v[14:15], v[194:195], v[254:255] op_sel_hi:[0,1,1]
	v_pk_fma_f32 v[8:9], v[14:15], v[192:193], v[252:253] op_sel_hi:[0,1,1]
	s_waitcnt lgkmcnt(5)
	v_pk_mul_f32 v[250:251], v[8:9], v[206:207]
	v_pk_mul_f32 v[252:253], v[136:137], v[218:219] op_sel:[1,0] op_sel_hi:[1,1]
	v_pk_fma_f32 v[250:251], v[10:11], v[208:209], v[250:251]
	v_pk_mul_f32 v[254:255], v[136:137], v[220:221] op_sel:[1,0] op_sel_hi:[1,1]
	v_add_f32_e32 v14, v250, v251
	v_pk_fma_f32 v[252:253], v[8:9], v[210:211], v[252:253]
	v_pk_fma_f32 v[254:255], v[10:11], v[212:213], v[254:255]
	v_add_f32_dpp v14, v14, v14 quad_perm:[1,0,3,2] row_mask:0xf bank_mask:0xf bound_ctrl:1
	v_pk_mul_f32 v[12:13], v[8:9], v[200:201]
	s_nop 0
	v_add_f32_dpp v14, v14, v14 quad_perm:[2,3,0,1] row_mask:0xf bank_mask:0xf bound_ctrl:1
	v_pk_fma_f32 v[12:13], v[10:11], v[202:203], v[12:13]
	s_nop 0
	v_add_f32_dpp v14, v14, v14 row_half_mirror row_mask:0xf bank_mask:0xf bound_ctrl:1
	v_add_f32_e32 v18, v12, v13
	s_nop 0
	v_add_f32_dpp v14, v14, v14 row_mirror row_mask:0xf bank_mask:0xf bound_ctrl:1
	v_pk_fma_f32 v[10:11], v[14:15], v[216:217], v[254:255] op_sel_hi:[0,1,1]
	v_pk_fma_f32 v[8:9], v[14:15], v[214:215], v[252:253] op_sel_hi:[0,1,1]
	ds_read_b128 v[184:187], v126 offset:4032
	ds_read_b128 v[196:199], v126 offset:4800
	ds_read_b128 v[188:191], v126 offset:4288
	ds_read_b128 v[200:203], v126 offset:5056
	ds_read_b128 v[192:195], v126 offset:4544
	s_waitcnt lgkmcnt(5)
	v_pk_mul_f32 v[250:251], v[8:9], v[228:229]
	v_pk_mul_f32 v[252:253], v[138:139], v[240:241] op_sel_hi:[0,1]
	v_pk_fma_f32 v[250:251], v[10:11], v[230:231], v[250:251]
	v_pk_mul_f32 v[254:255], v[138:139], v[242:243] op_sel_hi:[0,1]
	v_add_f32_e32 v14, v250, v251
	v_pk_fma_f32 v[252:253], v[8:9], v[232:233], v[252:253]
	v_pk_fma_f32 v[254:255], v[10:11], v[234:235], v[254:255]
	v_add_f32_dpp v14, v14, v14 quad_perm:[1,0,3,2] row_mask:0xf bank_mask:0xf bound_ctrl:1
	v_pk_mul_f32 v[12:13], v[8:9], v[222:223]
	s_nop 0
	v_add_f32_dpp v14, v14, v14 quad_perm:[2,3,0,1] row_mask:0xf bank_mask:0xf bound_ctrl:1
	v_pk_fma_f32 v[12:13], v[10:11], v[224:225], v[12:13]
	s_nop 0
	v_add_f32_dpp v14, v14, v14 row_half_mirror row_mask:0xf bank_mask:0xf bound_ctrl:1
	v_add_f32_e32 v19, v12, v13
	s_nop 0
	v_add_f32_dpp v14, v14, v14 row_mirror row_mask:0xf bank_mask:0xf bound_ctrl:1
	v_pk_fma_f32 v[10:11], v[14:15], v[238:239], v[254:255] op_sel_hi:[0,1,1]
	v_pk_fma_f32 v[8:9], v[14:15], v[236:237], v[252:253] op_sel_hi:[0,1,1]
	ds_read_b128 v[140:143], v127 offset:16
	ds_read_b128 v[206:209], v126 offset:5376
	ds_read_b128 v[218:221], v126 offset:6144
	ds_read_b128 v[210:213], v126 offset:5632
	ds_read_b128 v[222:225], v126 offset:6400
	ds_read_b128 v[214:217], v126 offset:5888
	s_waitcnt lgkmcnt(6)
	v_pk_mul_f32 v[250:251], v[8:9], v[184:185]
	v_pk_mul_f32 v[252:253], v[138:139], v[196:197] op_sel:[1,0] op_sel_hi:[1,1]
	v_pk_fma_f32 v[250:251], v[10:11], v[186:187], v[250:251]
	v_pk_mul_f32 v[254:255], v[138:139], v[198:199] op_sel:[1,0] op_sel_hi:[1,1]
	v_add_f32_e32 v14, v250, v251
	v_pk_fma_f32 v[252:253], v[8:9], v[188:189], v[252:253]
	v_pk_fma_f32 v[254:255], v[10:11], v[190:191], v[254:255]
	v_add_f32_dpp v14, v14, v14 quad_perm:[1,0,3,2] row_mask:0xf bank_mask:0xf bound_ctrl:1
	v_pk_mul_f32 v[12:13], v[8:9], v[244:245]
	s_nop 0
	v_add_f32_dpp v14, v14, v14 quad_perm:[2,3,0,1] row_mask:0xf bank_mask:0xf bound_ctrl:1
	v_pk_fma_f32 v[12:13], v[10:11], v[246:247], v[12:13]
	s_nop 0
	v_add_f32_dpp v14, v14, v14 row_half_mirror row_mask:0xf bank_mask:0xf bound_ctrl:1
	v_add_f32_e32 v20, v12, v13
	s_nop 0
	v_add_f32_dpp v14, v14, v14 row_mirror row_mask:0xf bank_mask:0xf bound_ctrl:1
	v_pk_fma_f32 v[10:11], v[14:15], v[194:195], v[254:255] op_sel_hi:[0,1,1]
	v_pk_fma_f32 v[8:9], v[14:15], v[192:193], v[252:253] op_sel_hi:[0,1,1]
	ds_read_b128 v[228:231], v126 offset:6720
	ds_read_b128 v[240:243], v126 offset:7488
	ds_read_b128 v[232:235], v126 offset:6976
	ds_read_b128 v[244:247], v126 offset:7744
	ds_read_b128 v[236:239], v126 offset:7232
	s_waitcnt lgkmcnt(5)
	v_pk_mul_f32 v[250:251], v[8:9], v[206:207]
	v_pk_mul_f32 v[252:253], v[140:141], v[218:219] op_sel_hi:[0,1]
	v_pk_fma_f32 v[250:251], v[10:11], v[208:209], v[250:251]
	v_pk_mul_f32 v[254:255], v[140:141], v[220:221] op_sel_hi:[0,1]
	v_add_f32_e32 v14, v250, v251
	v_pk_fma_f32 v[252:253], v[8:9], v[210:211], v[252:253]
	v_pk_fma_f32 v[254:255], v[10:11], v[212:213], v[254:255]
	v_add_f32_dpp v14, v14, v14 quad_perm:[1,0,3,2] row_mask:0xf bank_mask:0xf bound_ctrl:1
	v_pk_mul_f32 v[12:13], v[8:9], v[200:201]
	s_nop 0
	v_add_f32_dpp v14, v14, v14 quad_perm:[2,3,0,1] row_mask:0xf bank_mask:0xf bound_ctrl:1
	v_pk_fma_f32 v[12:13], v[10:11], v[202:203], v[12:13]
	s_nop 0
	v_add_f32_dpp v14, v14, v14 row_half_mirror row_mask:0xf bank_mask:0xf bound_ctrl:1
	v_add_f32_e32 v21, v12, v13
	s_nop 0
	v_add_f32_dpp v14, v14, v14 row_mirror row_mask:0xf bank_mask:0xf bound_ctrl:1
	v_pk_fma_f32 v[10:11], v[14:15], v[216:217], v[254:255] op_sel_hi:[0,1,1]
	v_pk_fma_f32 v[8:9], v[14:15], v[214:215], v[252:253] op_sel_hi:[0,1,1]
	ds_read_b128 v[184:187], v126 offset:8064
	ds_read_b128 v[196:199], v126 offset:8832
	ds_read_b128 v[188:191], v126 offset:8320
	ds_read_b128 v[200:203], v126 offset:9088
	ds_read_b128 v[192:195], v126 offset:8576
	s_waitcnt lgkmcnt(5)
	v_pk_mul_f32 v[250:251], v[8:9], v[228:229]
	v_pk_mul_f32 v[252:253], v[140:141], v[240:241] op_sel:[1,0] op_sel_hi:[1,1]
	v_pk_fma_f32 v[250:251], v[10:11], v[230:231], v[250:251]
	v_pk_mul_f32 v[254:255], v[140:141], v[242:243] op_sel:[1,0] op_sel_hi:[1,1]
	v_add_f32_e32 v14, v250, v251
	v_pk_fma_f32 v[252:253], v[8:9], v[232:233], v[252:253]
	v_pk_fma_f32 v[254:255], v[10:11], v[234:235], v[254:255]
	v_add_f32_dpp v14, v14, v14 quad_perm:[1,0,3,2] row_mask:0xf bank_mask:0xf bound_ctrl:1
	v_pk_mul_f32 v[12:13], v[8:9], v[222:223]
	s_nop 0
	v_add_f32_dpp v14, v14, v14 quad_perm:[2,3,0,1] row_mask:0xf bank_mask:0xf bound_ctrl:1
	v_pk_fma_f32 v[12:13], v[10:11], v[224:225], v[12:13]
	s_nop 0
	v_add_f32_dpp v14, v14, v14 row_half_mirror row_mask:0xf bank_mask:0xf bound_ctrl:1
	v_add_f32_e32 v22, v12, v13
	s_nop 0
	v_add_f32_dpp v14, v14, v14 row_mirror row_mask:0xf bank_mask:0xf bound_ctrl:1
	v_pk_fma_f32 v[10:11], v[14:15], v[238:239], v[254:255] op_sel_hi:[0,1,1]
	v_pk_fma_f32 v[8:9], v[14:15], v[236:237], v[252:253] op_sel_hi:[0,1,1]
	ds_read_b128 v[206:209], v126 offset:9408
	ds_read_b128 v[218:221], v126 offset:10176
	ds_read_b128 v[210:213], v126 offset:9664
	ds_read_b128 v[222:225], v126 offset:10432
	ds_read_b128 v[214:217], v126 offset:9920
	s_waitcnt lgkmcnt(5)
	v_pk_mul_f32 v[250:251], v[8:9], v[184:185]
	v_pk_mul_f32 v[252:253], v[142:143], v[196:197] op_sel_hi:[0,1]
	v_pk_fma_f32 v[250:251], v[10:11], v[186:187], v[250:251]
	v_pk_mul_f32 v[254:255], v[142:143], v[198:199] op_sel_hi:[0,1]
	v_add_f32_e32 v14, v250, v251
	v_pk_fma_f32 v[252:253], v[8:9], v[188:189], v[252:253]
	v_pk_fma_f32 v[254:255], v[10:11], v[190:191], v[254:255]
	v_add_f32_dpp v14, v14, v14 quad_perm:[1,0,3,2] row_mask:0xf bank_mask:0xf bound_ctrl:1
	v_pk_mul_f32 v[12:13], v[8:9], v[244:245]
	s_nop 0
	v_add_f32_dpp v14, v14, v14 quad_perm:[2,3,0,1] row_mask:0xf bank_mask:0xf bound_ctrl:1
	v_pk_fma_f32 v[12:13], v[10:11], v[246:247], v[12:13]
	s_nop 0
	v_add_f32_dpp v14, v14, v14 row_half_mirror row_mask:0xf bank_mask:0xf bound_ctrl:1
	v_add_f32_e32 v23, v12, v13
	s_nop 0
	v_add_f32_dpp v14, v14, v14 row_mirror row_mask:0xf bank_mask:0xf bound_ctrl:1
	v_pk_fma_f32 v[10:11], v[14:15], v[194:195], v[254:255] op_sel_hi:[0,1,1]
	v_pk_fma_f32 v[8:9], v[14:15], v[192:193], v[252:253] op_sel_hi:[0,1,1]
	ds_read_b128 v[136:139], v127 offset:32
	ds_read_b128 v[228:231], v126 offset:10752
	ds_read_b128 v[240:243], v126 offset:11520
	ds_read_b128 v[232:235], v126 offset:11008
	ds_read_b128 v[244:247], v126 offset:11776
	ds_read_b128 v[236:239], v126 offset:11264
	s_waitcnt lgkmcnt(6)
	v_pk_mul_f32 v[250:251], v[8:9], v[206:207]
	v_pk_mul_f32 v[252:253], v[142:143], v[218:219] op_sel:[1,0] op_sel_hi:[1,1]
	v_pk_fma_f32 v[250:251], v[10:11], v[208:209], v[250:251]
	v_pk_mul_f32 v[254:255], v[142:143], v[220:221] op_sel:[1,0] op_sel_hi:[1,1]
	v_add_f32_e32 v14, v250, v251
	v_pk_fma_f32 v[252:253], v[8:9], v[210:211], v[252:253]
	v_pk_fma_f32 v[254:255], v[10:11], v[212:213], v[254:255]
	v_add_f32_dpp v14, v14, v14 quad_perm:[1,0,3,2] row_mask:0xf bank_mask:0xf bound_ctrl:1
	v_pk_mul_f32 v[12:13], v[8:9], v[200:201]
	s_nop 0
	v_add_f32_dpp v14, v14, v14 quad_perm:[2,3,0,1] row_mask:0xf bank_mask:0xf bound_ctrl:1
	v_pk_fma_f32 v[12:13], v[10:11], v[202:203], v[12:13]
	s_nop 0
	v_add_f32_dpp v14, v14, v14 row_half_mirror row_mask:0xf bank_mask:0xf bound_ctrl:1
	v_add_f32_e32 v24, v12, v13
	s_nop 0
	v_add_f32_dpp v14, v14, v14 row_mirror row_mask:0xf bank_mask:0xf bound_ctrl:1
	v_pk_fma_f32 v[10:11], v[14:15], v[216:217], v[254:255] op_sel_hi:[0,1,1]
	v_pk_fma_f32 v[8:9], v[14:15], v[214:215], v[252:253] op_sel_hi:[0,1,1]
	ds_read_b128 v[184:187], v126 offset:12096
	ds_read_b128 v[196:199], v126 offset:12864
	ds_read_b128 v[188:191], v126 offset:12352
	ds_read_b128 v[200:203], v126 offset:13120
	ds_read_b128 v[192:195], v126 offset:12608
	s_waitcnt lgkmcnt(5)
	v_pk_mul_f32 v[250:251], v[8:9], v[228:229]
	v_pk_mul_f32 v[252:253], v[136:137], v[240:241] op_sel_hi:[0,1]
	v_pk_fma_f32 v[250:251], v[10:11], v[230:231], v[250:251]
	v_pk_mul_f32 v[254:255], v[136:137], v[242:243] op_sel_hi:[0,1]
	v_add_f32_e32 v14, v250, v251
	v_pk_fma_f32 v[252:253], v[8:9], v[232:233], v[252:253]
	v_pk_fma_f32 v[254:255], v[10:11], v[234:235], v[254:255]
	v_add_f32_dpp v14, v14, v14 quad_perm:[1,0,3,2] row_mask:0xf bank_mask:0xf bound_ctrl:1
	v_pk_mul_f32 v[12:13], v[8:9], v[222:223]
	s_nop 0
	v_add_f32_dpp v14, v14, v14 quad_perm:[2,3,0,1] row_mask:0xf bank_mask:0xf bound_ctrl:1
	v_pk_fma_f32 v[12:13], v[10:11], v[224:225], v[12:13]
	s_nop 0
	v_add_f32_dpp v14, v14, v14 row_half_mirror row_mask:0xf bank_mask:0xf bound_ctrl:1
	v_add_f32_e32 v25, v12, v13
	s_nop 0
	v_add_f32_dpp v14, v14, v14 row_mirror row_mask:0xf bank_mask:0xf bound_ctrl:1
	v_pk_fma_f32 v[10:11], v[14:15], v[238:239], v[254:255] op_sel_hi:[0,1,1]
	v_pk_fma_f32 v[8:9], v[14:15], v[236:237], v[252:253] op_sel_hi:[0,1,1]
	ds_read_b128 v[206:209], v126 offset:13440
	ds_read_b128 v[218:221], v126 offset:14208
	ds_read_b128 v[210:213], v126 offset:13696
	ds_read_b128 v[222:225], v126 offset:14464
	ds_read_b128 v[214:217], v126 offset:13952
	s_waitcnt vmcnt(0)
	s_xor_b32 s0, s11, 1
	v_lshl_add_u32 v170, s0, 10, v130
	s_mulk_i32 s0, 0x5400
	v_add_u32_e32 v82, s0, v79
	v_lshlrev_b32_e32 v34, 16, v74
	v_and_b32_e32 v35, 0xffff0000, v74
	v_lshlrev_b32_e32 v36, 16, v75
	v_and_b32_e32 v37, 0xffff0000, v75
	v_lshl_add_u32 v83, v50, 2, v82
	v_pk_mul_f32 v[38:39], v[0:1], v[34:35]
	v_pk_mul_f32 v[40:41], v[2:3], v[36:37]
	v_lshlrev_b32_e32 v120, 16, v72
	v_pk_mul_f32 v[42:43], v[78:79], v[38:39] op_sel_hi:[0,1] neg_lo:[1,0] neg_hi:[1,0]
	v_pk_mul_f32 v[44:45], v[78:79], v[40:41] op_sel_hi:[0,1] neg_lo:[1,0] neg_hi:[1,0]
	v_and_b32_e32 v121, 0xffff0000, v72
	v_lshlrev_b32_e32 v122, 16, v73
	v_and_b32_e32 v123, 0xffff0000, v73
	ds_write_b128 v83, v[42:45]
	v_lshlrev_b32_e32 v38, 16, v76
	v_and_b32_e32 v39, 0xffff0000, v76
	v_lshlrev_b32_e32 v40, 16, v77
	v_and_b32_e32 v41, 0xffff0000, v77
	v_pk_add_f32 v[38:39], v[38:39], 1.0 op_sel_hi:[1,0] neg_lo:[1,0] neg_hi:[1,0]
	v_pk_add_f32 v[40:41], v[40:41], 1.0 op_sel_hi:[1,0] neg_lo:[1,0] neg_hi:[1,0]
	v_lshl_add_u32 v85, v48, 2, v82
	ds_write_b128 v83, v[38:41] offset:256
	v_pk_mul_f32 v[38:39], v[42:43], v[120:121] neg_lo:[1,0] neg_hi:[1,0]
	v_pk_mul_f32 v[40:41], v[44:45], v[122:123] neg_lo:[1,0] neg_hi:[1,0]
	v_pk_add_f32 v[120:121], v[120:121], -1.0 op_sel_hi:[1,0]
	v_pk_add_f32 v[122:123], v[122:123], -1.0 op_sel_hi:[1,0]
	ds_write_b128 v83, v[38:41] offset:512
	v_pk_fma_f32 v[120:121], v[4:5], v[120:121], 1.0 op_sel_hi:[1,1,0]
	v_pk_fma_f32 v[122:123], v[6:7], v[122:123], 1.0 op_sel_hi:[1,1,0]
	v_lshlrev_b32_e32 v42, 16, v62
	v_and_b32_e32 v43, 0xffff0000, v62
	v_pk_mul_f32 v[120:121], v[120:121], v[34:35]
	v_pk_mul_f32 v[122:123], v[122:123], v[36:37]
	v_lshlrev_b32_e32 v44, 16, v63
	v_and_b32_e32 v45, 0xffff0000, v63
	v_lshlrev_b32_e32 v84, 16, v102
	ds_write_b128 v83, v[120:123] offset:768
	ds_write_b128 v83, v[42:45] offset:1024
	ds_write_b32 v85, v84 offset:1280
	ds_write_b32 v170, v84
	s_cmpk_eq_i32 s6, 0x20e0
	s_cbranch_scc1 .Lscan_pf_skip
	v_add_u32_e32 v131, v132, v131
	s_cmp_eq_u32 s10, 14
	s_cbranch_scc0 .Lscan_pf_nox
	v_mov_b32_e32 v131, v133

.Lscan_pf_skip:
	s_waitcnt lgkmcnt(12)
	v_pk_mul_f32 v[250:251], v[8:9], v[184:185]
	v_pk_mul_f32 v[252:253], v[136:137], v[196:197] op_sel:[1,0] op_sel_hi:[1,1]
	v_pk_fma_f32 v[250:251], v[10:11], v[186:187], v[250:251]
	v_pk_mul_f32 v[254:255], v[136:137], v[198:199] op_sel:[1,0] op_sel_hi:[1,1]
	v_add_f32_e32 v14, v250, v251
	v_pk_fma_f32 v[252:253], v[8:9], v[188:189], v[252:253]
	v_pk_fma_f32 v[254:255], v[10:11], v[190:191], v[254:255]
	v_add_f32_dpp v14, v14, v14 quad_perm:[1,0,3,2] row_mask:0xf bank_mask:0xf bound_ctrl:1
	v_pk_mul_f32 v[12:13], v[8:9], v[244:245]
	s_nop 0
	v_add_f32_dpp v14, v14, v14 quad_perm:[2,3,0,1] row_mask:0xf bank_mask:0xf bound_ctrl:1
	v_pk_fma_f32 v[12:13], v[10:11], v[246:247], v[12:13]
	s_nop 0
	v_add_f32_dpp v14, v14, v14 row_half_mirror row_mask:0xf bank_mask:0xf bound_ctrl:1
	v_add_f32_e32 v26, v12, v13
	s_nop 0
	v_add_f32_dpp v14, v14, v14 row_mirror row_mask:0xf bank_mask:0xf bound_ctrl:1
	v_pk_fma_f32 v[10:11], v[14:15], v[194:195], v[254:255] op_sel_hi:[0,1,1]
	v_pk_fma_f32 v[8:9], v[14:15], v[192:193], v[252:253] op_sel_hi:[0,1,1]
	ds_read_b128 v[228:231], v126 offset:14784
	ds_read_b128 v[240:243], v126 offset:15552
	ds_read_b128 v[232:235], v126 offset:15040
	ds_read_b128 v[244:247], v126 offset:15808
	ds_read_b128 v[236:239], v126 offset:15296
	s_waitcnt lgkmcnt(12)
	v_pk_mul_f32 v[250:251], v[8:9], v[206:207]
	v_pk_mul_f32 v[252:253], v[138:139], v[218:219] op_sel_hi:[0,1]
	v_pk_fma_f32 v[250:251], v[10:11], v[208:209], v[250:251]
	v_pk_mul_f32 v[254:255], v[138:139], v[220:221] op_sel_hi:[0,1]
	v_add_f32_e32 v14, v250, v251
	v_pk_fma_f32 v[252:253], v[8:9], v[210:211], v[252:253]
	v_pk_fma_f32 v[254:255], v[10:11], v[212:213], v[254:255]
	v_add_f32_dpp v14, v14, v14 quad_perm:[1,0,3,2] row_mask:0xf bank_mask:0xf bound_ctrl:1
	v_pk_mul_f32 v[12:13], v[8:9], v[200:201]
	s_nop 0
	v_add_f32_dpp v14, v14, v14 quad_perm:[2,3,0,1] row_mask:0xf bank_mask:0xf bound_ctrl:1
	v_pk_fma_f32 v[12:13], v[10:11], v[202:203], v[12:13]
	s_nop 0
	v_add_f32_dpp v14, v14, v14 row_half_mirror row_mask:0xf bank_mask:0xf bound_ctrl:1
	v_add_f32_e32 v27, v12, v13
	s_nop 0
	v_add_f32_dpp v14, v14, v14 row_mirror row_mask:0xf bank_mask:0xf bound_ctrl:1
	v_pk_fma_f32 v[10:11], v[14:15], v[216:217], v[254:255] op_sel_hi:[0,1,1]
	v_pk_fma_f32 v[8:9], v[14:15], v[214:215], v[252:253] op_sel_hi:[0,1,1]
	ds_read_b128 v[140:143], v127 offset:48
	ds_read_b128 v[184:187], v126 offset:16128
	ds_read_b128 v[196:199], v126 offset:16896
	ds_read_b128 v[188:191], v126 offset:16384
	ds_read_b128 v[200:203], v126 offset:17152
	ds_read_b128 v[192:195], v126 offset:16640
	s_waitcnt lgkmcnt(6)
	v_pk_mul_f32 v[250:251], v[8:9], v[228:229]
	v_pk_mul_f32 v[252:253], v[138:139], v[240:241] op_sel:[1,0] op_sel_hi:[1,1]
	v_pk_fma_f32 v[250:251], v[10:11], v[230:231], v[250:251]
	v_pk_mul_f32 v[254:255], v[138:139], v[242:243] op_sel:[1,0] op_sel_hi:[1,1]
	v_add_f32_e32 v14, v250, v251
	v_pk_fma_f32 v[252:253], v[8:9], v[232:233], v[252:253]
	v_pk_fma_f32 v[254:255], v[10:11], v[234:235], v[254:255]
	v_add_f32_dpp v14, v14, v14 quad_perm:[1,0,3,2] row_mask:0xf bank_mask:0xf bound_ctrl:1
	v_pk_mul_f32 v[12:13], v[8:9], v[222:223]
	s_nop 0
	v_add_f32_dpp v14, v14, v14 quad_perm:[2,3,0,1] row_mask:0xf bank_mask:0xf bound_ctrl:1
	v_pk_fma_f32 v[12:13], v[10:11], v[224:225], v[12:13]
	s_nop 0
	v_add_f32_dpp v14, v14, v14 row_half_mirror row_mask:0xf bank_mask:0xf bound_ctrl:1
	v_add_f32_e32 v28, v12, v13
	s_nop 0
	v_add_f32_dpp v14, v14, v14 row_mirror row_mask:0xf bank_mask:0xf bound_ctrl:1
	v_pk_fma_f32 v[10:11], v[14:15], v[238:239], v[254:255] op_sel_hi:[0,1,1]
	v_pk_fma_f32 v[8:9], v[14:15], v[236:237], v[252:253] op_sel_hi:[0,1,1]
	ds_read_b128 v[206:209], v126 offset:17472
	ds_read_b128 v[218:221], v126 offset:18240
	ds_read_b128 v[210:213], v126 offset:17728
	ds_read_b128 v[222:225], v126 offset:18496
	ds_read_b128 v[214:217], v126 offset:17984
	s_waitcnt lgkmcnt(5)
	v_pk_mul_f32 v[250:251], v[8:9], v[184:185]
	v_pk_mul_f32 v[252:253], v[140:141], v[196:197] op_sel_hi:[0,1]
	v_pk_fma_f32 v[250:251], v[10:11], v[186:187], v[250:251]
	v_pk_mul_f32 v[254:255], v[140:141], v[198:199] op_sel_hi:[0,1]
	v_add_f32_e32 v14, v250, v251
	v_pk_fma_f32 v[252:253], v[8:9], v[188:189], v[252:253]
	v_pk_fma_f32 v[254:255], v[10:11], v[190:191], v[254:255]
	v_add_f32_dpp v14, v14, v14 quad_perm:[1,0,3,2] row_mask:0xf bank_mask:0xf bound_ctrl:1
	v_pk_mul_f32 v[12:13], v[8:9], v[244:245]
	s_nop 0
	v_add_f32_dpp v14, v14, v14 quad_perm:[2,3,0,1] row_mask:0xf bank_mask:0xf bound_ctrl:1
	v_pk_fma_f32 v[12:13], v[10:11], v[246:247], v[12:13]
	s_nop 0
	v_add_f32_dpp v14, v14, v14 row_half_mirror row_mask:0xf bank_mask:0xf bound_ctrl:1
	v_add_f32_e32 v29, v12, v13
	s_nop 0
	v_add_f32_dpp v14, v14, v14 row_mirror row_mask:0xf bank_mask:0xf bound_ctrl:1
	v_pk_fma_f32 v[10:11], v[14:15], v[194:195], v[254:255] op_sel_hi:[0,1,1]
	v_pk_fma_f32 v[8:9], v[14:15], v[192:193], v[252:253] op_sel_hi:[0,1,1]
	ds_read_b128 v[228:231], v126 offset:18816
	ds_read_b128 v[240:243], v126 offset:19584
	ds_read_b128 v[232:235], v126 offset:19072
	ds_read_b128 v[244:247], v126 offset:19840
	ds_read_b128 v[236:239], v126 offset:19328
	s_waitcnt lgkmcnt(5)
	v_pk_mul_f32 v[250:251], v[8:9], v[206:207]
	v_pk_mul_f32 v[252:253], v[140:141], v[218:219] op_sel:[1,0] op_sel_hi:[1,1]
	v_pk_fma_f32 v[250:251], v[10:11], v[208:209], v[250:251]
	v_pk_mul_f32 v[254:255], v[140:141], v[220:221] op_sel:[1,0] op_sel_hi:[1,1]
	v_add_f32_e32 v14, v250, v251
	v_pk_fma_f32 v[252:253], v[8:9], v[210:211], v[252:253]
	v_pk_fma_f32 v[254:255], v[10:11], v[212:213], v[254:255]
	v_add_f32_dpp v14, v14, v14 quad_perm:[1,0,3,2] row_mask:0xf bank_mask:0xf bound_ctrl:1
	v_pk_mul_f32 v[12:13], v[8:9], v[200:201]
	s_nop 0
	v_add_f32_dpp v14, v14, v14 quad_perm:[2,3,0,1] row_mask:0xf bank_mask:0xf bound_ctrl:1
	v_pk_fma_f32 v[12:13], v[10:11], v[202:203], v[12:13]
	s_nop 0
	v_add_f32_dpp v14, v14, v14 row_half_mirror row_mask:0xf bank_mask:0xf bound_ctrl:1
	v_add_f32_e32 v30, v12, v13
	s_nop 0
	v_add_f32_dpp v14, v14, v14 row_mirror row_mask:0xf bank_mask:0xf bound_ctrl:1
	v_pk_fma_f32 v[10:11], v[14:15], v[216:217], v[254:255] op_sel_hi:[0,1,1]
	v_pk_fma_f32 v[8:9], v[14:15], v[214:215], v[252:253] op_sel_hi:[0,1,1]
	ds_read_b128 v[184:187], v126 offset:20160
	ds_read_b128 v[196:199], v126 offset:20928
	ds_read_b128 v[188:191], v126 offset:20416
	ds_read_b128 v[200:203], v126 offset:21184
	ds_read_b128 v[192:195], v126 offset:20672
	s_waitcnt lgkmcnt(5)
	v_pk_mul_f32 v[250:251], v[8:9], v[228:229]
	v_pk_mul_f32 v[252:253], v[142:143], v[240:241] op_sel_hi:[0,1]
	v_pk_fma_f32 v[250:251], v[10:11], v[230:231], v[250:251]
	v_pk_mul_f32 v[254:255], v[142:143], v[242:243] op_sel_hi:[0,1]
	v_add_f32_e32 v14, v250, v251
	v_pk_fma_f32 v[252:253], v[8:9], v[232:233], v[252:253]
	v_pk_fma_f32 v[254:255], v[10:11], v[234:235], v[254:255]
	v_add_f32_dpp v14, v14, v14 quad_perm:[1,0,3,2] row_mask:0xf bank_mask:0xf bound_ctrl:1
	v_pk_mul_f32 v[12:13], v[8:9], v[222:223]
	s_nop 0
	v_add_f32_dpp v14, v14, v14 quad_perm:[2,3,0,1] row_mask:0xf bank_mask:0xf bound_ctrl:1
	v_pk_fma_f32 v[12:13], v[10:11], v[224:225], v[12:13]
	s_nop 0
	v_add_f32_dpp v14, v14, v14 row_half_mirror row_mask:0xf bank_mask:0xf bound_ctrl:1
	v_add_f32_e32 v31, v12, v13
	s_nop 0
	v_add_f32_dpp v14, v14, v14 row_mirror row_mask:0xf bank_mask:0xf bound_ctrl:1
	v_pk_fma_f32 v[10:11], v[14:15], v[238:239], v[254:255] op_sel_hi:[0,1,1]
	v_pk_fma_f32 v[8:9], v[14:15], v[236:237], v[252:253] op_sel_hi:[0,1,1]
	s_waitcnt lgkmcnt(0)
	v_pk_mul_f32 v[250:251], v[8:9], v[184:185]
	v_pk_mul_f32 v[252:253], v[142:143], v[196:197] op_sel:[1,0] op_sel_hi:[1,1]
	v_pk_fma_f32 v[250:251], v[10:11], v[186:187], v[250:251]
	v_pk_mul_f32 v[254:255], v[142:143], v[198:199] op_sel:[1,0] op_sel_hi:[1,1]
	v_add_f32_e32 v14, v250, v251
	v_pk_fma_f32 v[252:253], v[8:9], v[188:189], v[252:253]
	v_pk_fma_f32 v[254:255], v[10:11], v[190:191], v[254:255]
	v_add_f32_dpp v14, v14, v14 quad_perm:[1,0,3,2] row_mask:0xf bank_mask:0xf bound_ctrl:1
	v_pk_mul_f32 v[12:13], v[8:9], v[244:245]
	s_nop 0
	v_add_f32_dpp v14, v14, v14 quad_perm:[2,3,0,1] row_mask:0xf bank_mask:0xf bound_ctrl:1
	v_pk_fma_f32 v[12:13], v[10:11], v[246:247], v[12:13]
	s_nop 0
	v_add_f32_dpp v14, v14, v14 row_half_mirror row_mask:0xf bank_mask:0xf bound_ctrl:1
	v_add_f32_e32 v32, v12, v13
	s_nop 0
	v_add_f32_dpp v14, v14, v14 row_mirror row_mask:0xf bank_mask:0xf bound_ctrl:1
	v_pk_fma_f32 v[10:11], v[14:15], v[194:195], v[254:255] op_sel_hi:[0,1,1]
	v_pk_fma_f32 v[8:9], v[14:15], v[192:193], v[252:253] op_sel_hi:[0,1,1]
	v_pk_mul_f32 v[12:13], v[8:9], v[200:201]
	v_add_f32_dpp v34, v18, v18 row_mirror row_mask:0xf bank_mask:0x3 bound_ctrl:1
	v_pk_fma_f32 v[12:13], v[10:11], v[202:203], v[12:13]
	v_add_f32_dpp v35, v19, v19 row_mirror row_mask:0xf bank_mask:0x3 bound_ctrl:1
	v_add_f32_dpp v36, v20, v20 row_mirror row_mask:0xf bank_mask:0x3 bound_ctrl:1
	v_add_f32_e32 v33, v12, v13
	v_add_f32_dpp v37, v21, v21 row_mirror row_mask:0xf bank_mask:0x3 bound_ctrl:1
	v_add_f32_dpp v38, v22, v22 row_mirror row_mask:0xf bank_mask:0x3 bound_ctrl:1
	v_add_f32_dpp v39, v23, v23 row_mirror row_mask:0xf bank_mask:0x3 bound_ctrl:1
	v_add_f32_dpp v40, v24, v24 row_mirror row_mask:0xf bank_mask:0x3 bound_ctrl:1
	v_add_f32_dpp v41, v25, v25 row_mirror row_mask:0xf bank_mask:0x3 bound_ctrl:1
	v_add_f32_dpp v34, v26, v26 row_mirror row_mask:0xf bank_mask:0xc bound_ctrl:1
	v_add_f32_dpp v35, v27, v27 row_mirror row_mask:0xf bank_mask:0xc bound_ctrl:1
	v_add_f32_dpp v36, v28, v28 row_mirror row_mask:0xf bank_mask:0xc bound_ctrl:1
	v_add_f32_dpp v37, v29, v29 row_mirror row_mask:0xf bank_mask:0xc bound_ctrl:1
	v_add_f32_dpp v38, v30, v30 row_mirror row_mask:0xf bank_mask:0xc bound_ctrl:1
	v_add_f32_dpp v39, v31, v31 row_mirror row_mask:0xf bank_mask:0xc bound_ctrl:1
	v_add_f32_dpp v40, v32, v32 row_mirror row_mask:0xf bank_mask:0xc bound_ctrl:1
	v_add_f32_dpp v41, v33, v33 row_mirror row_mask:0xf bank_mask:0xc bound_ctrl:1
	v_add_f32_dpp v42, v34, v34 row_half_mirror row_mask:0xf bank_mask:0x5 bound_ctrl:1
	v_add_f32_dpp v43, v35, v35 row_half_mirror row_mask:0xf bank_mask:0x5 bound_ctrl:1
	v_add_f32_dpp v44, v36, v36 row_half_mirror row_mask:0xf bank_mask:0x5 bound_ctrl:1
	v_add_f32_dpp v45, v37, v37 row_half_mirror row_mask:0xf bank_mask:0x5 bound_ctrl:1
	v_add_f32_dpp v42, v38, v38 row_half_mirror row_mask:0xf bank_mask:0xa bound_ctrl:1
	v_add_f32_dpp v43, v39, v39 row_half_mirror row_mask:0xf bank_mask:0xa bound_ctrl:1
	v_add_f32_dpp v44, v40, v40 row_half_mirror row_mask:0xf bank_mask:0xa bound_ctrl:1
	v_add_f32_dpp v45, v41, v41 row_half_mirror row_mask:0xf bank_mask:0xa bound_ctrl:1
	v_cndmask_b32_e64 v80, v44, v42, s[42:43]
	v_cndmask_b32_e64 v121, v42, v44, s[42:43]
	v_cndmask_b32_e64 v82, v45, v43, s[42:43]
	v_cndmask_b32_e64 v122, v43, v45, s[42:43]
	s_nop 0
	s_nop 0
	v_add_f32_dpp v13, v121, v80 quad_perm:[2,3,0,1] row_mask:0xf bank_mask:0xf bound_ctrl:1
	v_add_f32_dpp v14, v122, v82 quad_perm:[2,3,0,1] row_mask:0xf bank_mask:0xf bound_ctrl:1
	v_cndmask_b32_e64 v12, v13, v14, s[44:45]
	v_cndmask_b32_e64 v13, v14, v13, s[44:45]
	v_lshl_add_u32 v16, v100, 11, v99
	v_add_u32_e32 v100, v132, v100
	v_add_f32_dpp v13, v12, v13 quad_perm:[1,0,3,2] row_mask:0xf bank_mask:0xf bound_ctrl:1
	s_cmp_eq_u32 s10, 15
	s_cbranch_scc0 .Lscan_tail_nox
	v_mov_b32_e32 v100, v101
